# MLA fast loop: fixed m=0 (no running max/sub) + end-of-unit l-range guard with WG-collective redo via original loop
# speedup vs baseline: 1.0287x; 1.0287x over previous
.LBB0_952:
	s_or_b64 exec, exec, s[0:1]
	s_add_u32 s8, s88, 0x2200000
	s_addc_u32 s9, s89, 0
	s_mov_b32 s2, s90
	s_mov_b32 s3, s92
	s_waitcnt lgkmcnt(0)
	s_barrier
	s_cmpk_gt_i32 s3, 0x1ff
	s_cbranch_scc1 .LBB0_978
	s_add_u32 s4, s88, 0x1c800080
	s_addc_u32 s5, s89, 0
	s_lshl_b32 s26, s3, 3
	s_lshl_b32 s27, s2, 3
	s_add_u32 s28, s88, 0x19803000
	s_addc_u32 s29, s89, 0
	v_mov_b32_e32 v1, 0
	s_movk_i32 s30, 0xc0
	s_movk_i32 s31, 0x1000
	s_mov_b32 s7, 0
	s_movk_i32 s34, 0x100
	v_mov_b32_e32 v204, 0xffffff00
	v_mov_b32_e32 v205, 0x100
	s_mov_b32 s35, 0x2aaaaaab
	s_mov_b32 s38, 0xffffff4
	s_movk_i32 s39, 0xd0
	s_movk_i32 s48, 0x48
	s_movk_i32 s49, 0x90
	s_mov_b32 s50, 0xf149f2ca
	s_mov_b32 s51, 0x41000000
	s_mov_b64 s[10:11], 0x80
	s_mov_b64 s[12:13], 0x3000
	s_movk_i32 s52, 0x1400
	s_mov_b64 s[14:15], 0x28000
	s_mov_b32 s99, 0
	s_branch .LBB0_955
.LBB0_954:
	s_or_b64 exec, exec, s[44:45]
	s_lshl_b32 s0, s33, 6
	s_lshl_b32 s6, s0, 1
	v_lshl_add_u64 v[4:5], v[12:13], 0, s[6:7]
	v_lshl_add_u64 v[4:5], v[4:5], 0, v[0:1]
	v_lshl_add_u64 v[4:5], v[4:5], 0, s[14:15]
	global_load_dwordx4 v[6:9], v[4:5], off offset:3072
	v_lshlrev_b64 v[2:3], 11, v[2:3]
	v_lshl_add_u64 v[2:3], s[42:43], 0, v[2:3]
	v_lshl_add_u64 v[2:3], v[2:3], 0, v[0:1]
	s_add_i32 s3, s3, s2
	s_add_i32 s26, s26, s27
	s_cmpk_gt_i32 s3, 0x1ff
	s_waitcnt vmcnt(0)
	v_mov_b32_e32 v0, v8
	v_mov_b32_e32 v8, v9
	s_nop 0
	v_permlane32_swap_b32_e32 v6, v0
	v_permlane32_swap_b32_e32 v7, v8
	v_lshlrev_b32_e32 v9, 16, v6
	v_and_b32_e32 v6, 0xffff0000, v6
	v_lshlrev_b32_e32 v10, 16, v7
	v_and_b32_e32 v7, 0xffff0000, v7
	v_lshlrev_b32_e32 v11, 16, v0
	v_and_b32_e32 v0, 0xffff0000, v0
	v_lshlrev_b32_e32 v12, 16, v8
	v_and_b32_e32 v8, 0xffff0000, v8
	v_mul_f32_e32 v13, 0xbfb8aa3b, v9
	v_mul_f32_e32 v30, 0xbfb8aa3b, v6
	v_mul_f32_e32 v48, 0xbfb8aa3b, v7
	v_mul_f32_e32 v31, 0xbfb8aa3b, v10
	v_mul_f32_e32 v49, 0xbfb8aa3b, v11
	v_mul_f32_e32 v50, 0xbfb8aa3b, v0
	v_mul_f32_e32 v51, 0xbfb8aa3b, v12
	v_mul_f32_e32 v52, 0xbfb8aa3b, v8
	v_exp_f32_e32 v13, v13
	v_exp_f32_e32 v30, v30
	v_exp_f32_e32 v48, v48
	v_exp_f32_e32 v31, v31
	v_exp_f32_e32 v49, v49
	v_exp_f32_e32 v50, v50
	v_exp_f32_e32 v51, v51
	v_exp_f32_e32 v52, v52
	v_add_f32_e32 v13, 1.0, v13
	v_add_f32_e32 v30, 1.0, v30
	v_add_f32_e32 v48, 1.0, v48
	v_add_f32_e32 v31, 1.0, v31
	v_add_f32_e32 v49, 1.0, v49
	v_add_f32_e32 v50, 1.0, v50
	v_add_f32_e32 v51, 1.0, v51
	v_add_f32_e32 v52, 1.0, v52
	v_rcp_f32_e32 v13, v13
	v_rcp_f32_e32 v30, v30
	v_rcp_f32_e32 v48, v48
	v_rcp_f32_e32 v31, v31
	v_rcp_f32_e32 v49, v49
	v_rcp_f32_e32 v50, v50
	v_rcp_f32_e32 v51, v51
	v_rcp_f32_e32 v52, v52
	v_mul_f32_e32 v9, v13, v9
	v_mul_f32_e32 v6, v30, v6
	v_mul_f32_e32 v7, v48, v7
	v_mul_f32_e32 v10, v31, v10
	v_mul_f32_e32 v11, v49, v11
	v_mul_f32_e32 v0, v50, v0
	v_mul_f32_e32 v12, v51, v12
	v_mul_f32_e32 v8, v52, v8
	v_mul_f32_e32 v9, v32, v9
	v_mul_f32_e32 v6, v33, v6
	v_mul_f32_e32 v7, v35, v7
	v_mul_f32_e32 v10, v34, v10
	v_mul_f32_e32 v11, v36, v11
	v_mul_f32_e32 v0, v37, v0
	v_mul_f32_e32 v12, v38, v12
	v_mul_f32_e32 v13, v39, v8
	v_cvt_pk_bf16_f32 v6, v9, v6
	v_cvt_pk_bf16_f32 v7, v10, v7
	v_cvt_pk_bf16_f32 v8, v11, v0
	v_cvt_pk_bf16_f32 v9, v12, v13
	s_nop 0
	v_permlane32_swap_b32_e32 v6, v8
	v_permlane32_swap_b32_e32 v7, v9
	global_store_dwordx4 v[2:3], v[6:9], off
	global_load_dwordx4 v[6:9], v[4:5], off offset:3104
	s_waitcnt vmcnt(0)
	v_mov_b32_e32 v0, v8
	v_mov_b32_e32 v8, v9
	s_nop 0
	v_permlane32_swap_b32_e32 v6, v0
	v_permlane32_swap_b32_e32 v7, v8
	v_lshlrev_b32_e32 v9, 16, v6
	v_and_b32_e32 v6, 0xffff0000, v6
	v_lshlrev_b32_e32 v10, 16, v7
	v_and_b32_e32 v7, 0xffff0000, v7
	v_lshlrev_b32_e32 v11, 16, v0
	v_and_b32_e32 v0, 0xffff0000, v0
	v_lshlrev_b32_e32 v12, 16, v8
	v_and_b32_e32 v8, 0xffff0000, v8
	v_mul_f32_e32 v13, 0xbfb8aa3b, v9
	v_mul_f32_e32 v30, 0xbfb8aa3b, v6
	v_mul_f32_e32 v32, 0xbfb8aa3b, v7
	v_mul_f32_e32 v31, 0xbfb8aa3b, v10
	v_mul_f32_e32 v33, 0xbfb8aa3b, v11
	v_mul_f32_e32 v34, 0xbfb8aa3b, v0
	v_mul_f32_e32 v35, 0xbfb8aa3b, v12
	v_mul_f32_e32 v36, 0xbfb8aa3b, v8
	v_exp_f32_e32 v13, v13
	v_exp_f32_e32 v30, v30
	v_exp_f32_e32 v32, v32
	v_exp_f32_e32 v31, v31
	v_exp_f32_e32 v33, v33
	v_exp_f32_e32 v34, v34
	v_exp_f32_e32 v35, v35
	v_exp_f32_e32 v36, v36
	v_add_f32_e32 v13, 1.0, v13
	v_add_f32_e32 v30, 1.0, v30
	v_add_f32_e32 v32, 1.0, v32
	v_add_f32_e32 v31, 1.0, v31
	v_add_f32_e32 v33, 1.0, v33
	v_add_f32_e32 v34, 1.0, v34
	v_add_f32_e32 v35, 1.0, v35
	v_add_f32_e32 v36, 1.0, v36
	v_rcp_f32_e32 v13, v13
	v_rcp_f32_e32 v30, v30
	v_rcp_f32_e32 v32, v32
	v_rcp_f32_e32 v31, v31
	v_rcp_f32_e32 v33, v33
	v_rcp_f32_e32 v34, v34
	v_rcp_f32_e32 v35, v35
	v_rcp_f32_e32 v36, v36
	v_mul_f32_e32 v9, v13, v9
	v_mul_f32_e32 v6, v30, v6
	v_mul_f32_e32 v7, v32, v7
	v_mul_f32_e32 v10, v31, v10
	v_mul_f32_e32 v11, v33, v11
	v_mul_f32_e32 v0, v34, v0
	v_mul_f32_e32 v12, v35, v12
	v_mul_f32_e32 v8, v36, v8
	v_mul_f32_e32 v9, v40, v9
	v_mul_f32_e32 v6, v41, v6
	v_mul_f32_e32 v7, v43, v7
	v_mul_f32_e32 v10, v42, v10
	v_mul_f32_e32 v11, v44, v11
	v_mul_f32_e32 v0, v45, v0
	v_mul_f32_e32 v12, v46, v12
	v_mul_f32_e32 v13, v47, v8
	v_cvt_pk_bf16_f32 v6, v9, v6
	v_cvt_pk_bf16_f32 v7, v10, v7
	v_cvt_pk_bf16_f32 v8, v11, v0
	v_cvt_pk_bf16_f32 v9, v12, v13
	s_nop 0
	v_permlane32_swap_b32_e32 v6, v8
	v_permlane32_swap_b32_e32 v7, v9
	global_store_dwordx4 v[2:3], v[6:9], off offset:32
	global_load_dwordx4 v[6:9], v[4:5], off offset:3136
	s_waitcnt vmcnt(0)
	v_mov_b32_e32 v0, v8
	v_mov_b32_e32 v8, v9
	s_nop 0
	v_permlane32_swap_b32_e32 v6, v0
	v_permlane32_swap_b32_e32 v7, v8
	v_lshlrev_b32_e32 v9, 16, v6
	v_and_b32_e32 v6, 0xffff0000, v6
	v_lshlrev_b32_e32 v10, 16, v7
	v_and_b32_e32 v7, 0xffff0000, v7
	v_lshlrev_b32_e32 v11, 16, v0
	v_and_b32_e32 v0, 0xffff0000, v0
	v_lshlrev_b32_e32 v12, 16, v8
	v_and_b32_e32 v8, 0xffff0000, v8
	v_mul_f32_e32 v13, 0xbfb8aa3b, v9
	v_mul_f32_e32 v30, 0xbfb8aa3b, v6
	v_mul_f32_e32 v32, 0xbfb8aa3b, v7
	v_mul_f32_e32 v31, 0xbfb8aa3b, v10
	v_mul_f32_e32 v33, 0xbfb8aa3b, v11
	v_mul_f32_e32 v34, 0xbfb8aa3b, v0
	v_mul_f32_e32 v35, 0xbfb8aa3b, v12
	v_mul_f32_e32 v36, 0xbfb8aa3b, v8
	v_exp_f32_e32 v13, v13
	v_exp_f32_e32 v30, v30
	v_exp_f32_e32 v32, v32
	v_exp_f32_e32 v31, v31
	v_exp_f32_e32 v33, v33
	v_exp_f32_e32 v34, v34
	v_exp_f32_e32 v35, v35
	v_exp_f32_e32 v36, v36
	v_add_f32_e32 v13, 1.0, v13
	v_add_f32_e32 v30, 1.0, v30
	v_add_f32_e32 v32, 1.0, v32
	v_add_f32_e32 v31, 1.0, v31
	v_add_f32_e32 v33, 1.0, v33
	v_add_f32_e32 v34, 1.0, v34
	v_add_f32_e32 v35, 1.0, v35
	v_add_f32_e32 v36, 1.0, v36
	v_rcp_f32_e32 v13, v13
	v_rcp_f32_e32 v30, v30
	v_rcp_f32_e32 v32, v32
	v_rcp_f32_e32 v31, v31
	v_rcp_f32_e32 v33, v33
	v_rcp_f32_e32 v34, v34
	v_rcp_f32_e32 v35, v35
	v_rcp_f32_e32 v36, v36
	v_mul_f32_e32 v9, v13, v9
	v_mul_f32_e32 v6, v30, v6
	v_mul_f32_e32 v7, v32, v7
	v_mul_f32_e32 v10, v31, v10
	v_mul_f32_e32 v11, v33, v11
	v_mul_f32_e32 v0, v34, v0
	v_mul_f32_e32 v12, v35, v12
	v_mul_f32_e32 v8, v36, v8
	v_mul_f32_e32 v9, v16, v9
	v_mul_f32_e32 v6, v17, v6
	v_mul_f32_e32 v7, v19, v7
	v_mul_f32_e32 v10, v18, v10
	v_mul_f32_e32 v11, v20, v11
	v_mul_f32_e32 v0, v21, v0
	v_mul_f32_e32 v12, v22, v12
	v_mul_f32_e32 v13, v23, v8
	v_cvt_pk_bf16_f32 v6, v9, v6
	v_cvt_pk_bf16_f32 v7, v10, v7
	v_cvt_pk_bf16_f32 v8, v11, v0
	v_cvt_pk_bf16_f32 v9, v12, v13
	s_nop 0
	v_permlane32_swap_b32_e32 v6, v8
	v_permlane32_swap_b32_e32 v7, v9
	global_store_dwordx4 v[2:3], v[6:9], off offset:64
	global_load_dwordx4 v[4:7], v[4:5], off offset:3168
	s_waitcnt vmcnt(0)
	v_mov_b32_e32 v0, v6
	v_mov_b32_e32 v6, v7
	s_nop 0
	v_permlane32_swap_b32_e32 v4, v0
	v_permlane32_swap_b32_e32 v5, v6
	v_lshlrev_b32_e32 v7, 16, v4
	v_and_b32_e32 v4, 0xffff0000, v4
	v_lshlrev_b32_e32 v8, 16, v5
	v_and_b32_e32 v5, 0xffff0000, v5
	v_lshlrev_b32_e32 v9, 16, v0
	v_and_b32_e32 v0, 0xffff0000, v0
	v_lshlrev_b32_e32 v10, 16, v6
	v_and_b32_e32 v6, 0xffff0000, v6
	v_mul_f32_e32 v11, 0xbfb8aa3b, v7
	v_mul_f32_e32 v12, 0xbfb8aa3b, v4
	v_mul_f32_e32 v16, 0xbfb8aa3b, v5
	v_mul_f32_e32 v13, 0xbfb8aa3b, v8
	v_mul_f32_e32 v17, 0xbfb8aa3b, v9
	v_mul_f32_e32 v18, 0xbfb8aa3b, v0
	v_mul_f32_e32 v19, 0xbfb8aa3b, v10
	v_mul_f32_e32 v20, 0xbfb8aa3b, v6
	v_exp_f32_e32 v11, v11
	v_exp_f32_e32 v12, v12
	v_exp_f32_e32 v16, v16
	v_exp_f32_e32 v13, v13
	v_exp_f32_e32 v17, v17
	v_exp_f32_e32 v18, v18
	v_exp_f32_e32 v19, v19
	v_exp_f32_e32 v20, v20
	v_add_f32_e32 v11, 1.0, v11
	v_add_f32_e32 v12, 1.0, v12
	v_add_f32_e32 v16, 1.0, v16
	v_add_f32_e32 v13, 1.0, v13
	v_add_f32_e32 v17, 1.0, v17
	v_add_f32_e32 v18, 1.0, v18
	v_add_f32_e32 v19, 1.0, v19
	v_add_f32_e32 v20, 1.0, v20
	v_rcp_f32_e32 v11, v11
	v_rcp_f32_e32 v12, v12
	v_rcp_f32_e32 v16, v16
	v_rcp_f32_e32 v13, v13
	v_rcp_f32_e32 v17, v17
	v_rcp_f32_e32 v18, v18
	v_rcp_f32_e32 v19, v19
	v_rcp_f32_e32 v20, v20
	v_mul_f32_e32 v7, v11, v7
	v_mul_f32_e32 v4, v12, v4
	v_mul_f32_e32 v5, v16, v5
	v_mul_f32_e32 v8, v13, v8
	v_mul_f32_e32 v9, v17, v9
	v_mul_f32_e32 v0, v18, v0
	v_mul_f32_e32 v10, v19, v10
	v_mul_f32_e32 v6, v20, v6
	v_mul_f32_e32 v7, v24, v7
	v_mul_f32_e32 v4, v25, v4
	v_mul_f32_e32 v5, v27, v5
	v_mul_f32_e32 v8, v26, v8
	v_mul_f32_e32 v9, v28, v9
	v_mul_f32_e32 v0, v29, v0
	v_mul_f32_e32 v10, v14, v10
	v_mul_f32_e32 v11, v15, v6
	v_cvt_pk_bf16_f32 v4, v7, v4
	v_cvt_pk_bf16_f32 v5, v8, v5
	v_cvt_pk_bf16_f32 v6, v9, v0
	v_cvt_pk_bf16_f32 v7, v10, v11
	s_nop 0
	v_permlane32_swap_b32_e32 v4, v6
	v_permlane32_swap_b32_e32 v5, v7
	global_store_dwordx4 v[2:3], v[4:7], off offset:96
	v_cmp_gt_u32_e32 vcc, 0x21800000, v242
	s_mov_b64 s[100:101], vcc
	v_cmp_lt_u32_e32 vcc, 0x71800000, v243
	s_or_b64 s[100:101], s[100:101], vcc
	s_cmp_lg_u64 s[100:101], 0
	s_cbranch_scc0 .Lg_nowrite
	v_mov_b32_e32 v239, 1
	ds_write_b32 v238, v239
.Lg_nowrite:
	s_waitcnt lgkmcnt(0)
	s_barrier
	ds_read_b32 v239, v238
	s_waitcnt lgkmcnt(0)
	v_readfirstlane_b32 s98, v239
	s_cmp_eq_u32 s98, 0
	s_cbranch_scc1 .Lg_ok
	s_cmp_lg_u32 s99, 0
	s_cbranch_scc1 .Lg_ok
	s_mov_b32 s99, 1
	s_sub_i32 s3, s3, s2
	s_sub_i32 s26, s26, s27
	s_branch .LBB0_955
.Lg_ok:
	s_mov_b32 s99, 0
	s_cmpk_gt_i32 s3, 0x1ff
	s_cbranch_scc1 .LBB0_978
.LBB0_955:
	s_lshl_b32 s0, s3, 3
	s_and_b32 s0, s0, 56
	s_ashr_i32 s53, s3, 6
	s_add_i32 s40, s0, s53
	v_readlane_b32 s0, v254, 3
	s_ashr_i32 s41, s40, 31
	v_mbcnt_lo_u32_b32 v0, -1, 0
	v_mbcnt_hi_u32_b32 v0, -1, v0
	s_lshl_b64 s[24:25], s[40:41], 19
	v_or_b32_e32 v12, s0, v0
	s_lshl_b64 s[0:1], s[40:41], 12
	s_lshl_b32 s41, s3, 6
	s_and_b32 s41, s41, 0xe00
	v_and_b32_e32 v0, 0xffffffc0, v12
	v_add_u32_e32 v196, s41, v0
	v_bfe_u32 v208, v12, 5, 1
	v_ashrrev_i32_e32 v197, 31, v196
	v_and_b32_e32 v209, 31, v12
	v_lshl_add_u64 v[2:3], s[0:1], 0, v[196:197]
	v_lshlrev_b32_e32 v0, 4, v208
	v_or_b32_e32 v2, v2, v209
	v_lshl_add_u64 v[4:5], s[74:75], 0, v[0:1]
	v_mad_u64_u32 v[4:5], s[0:1], v2, s30, v[4:5]
	v_mad_i32_i24 v5, v3, s30, v5
	v_add_co_u32_e32 v2, vcc, s31, v4
	s_mul_i32 s33, s40, 0xc0000
	s_nop 0
	v_addc_co_u32_e32 v3, vcc, 0, v5, vcc
	global_load_dwordx4 v[188:191], v[4:5], off
	global_load_dwordx4 v[184:187], v[4:5], off offset:32
	global_load_dwordx4 v[180:183], v[4:5], off offset:64
	global_load_dwordx4 v[172:175], v[4:5], off offset:96
	global_load_dwordx4 v[160:163], v[4:5], off offset:128
	global_load_dwordx4 v[156:159], v[4:5], off offset:160
	global_load_dwordx4 v[176:179], v[2:3], off offset:2048
	global_load_dwordx4 v[168:171], v[2:3], off offset:2080
	global_load_dwordx4 v[164:167], v[2:3], off offset:2112
	global_load_dwordx4 v[152:155], v[2:3], off offset:2144
	global_load_dwordx4 v[148:151], v[2:3], off offset:2176
	global_load_dwordx4 v[144:147], v[2:3], off offset:2208
	s_mul_hi_i32 s6, s40, 0xc0000
	s_add_u32 s42, s22, s33
	v_lshlrev_b32_e32 v14, 3, v12
	s_addc_u32 s43, s23, s6
	v_ashrrev_i32_e32 v15, 31, v14
	v_lshl_add_u64 v[2:3], v[14:15], 1, s[42:43]
	s_barrier
	v_mov_b32_e32 v238, 0x10000
	ds_write_b32 v238, v1
	v_mov_b32_e32 v242, 0x7fffffff
	v_mov_b32_e32 v243, 0
	global_load_dwordx4 v[4:7], v[2:3], off
	v_cmp_gt_i32_e64 s[0:1], s34, v12
	s_add_u32 s24, s46, s24
	s_addc_u32 s25, s47, s25
	v_cndmask_b32_e64 v0, v204, v205, s[0:1]
	v_add_u32_e32 v0, v0, v12
	v_ashrrev_i32_e32 v18, 3, v0
	v_ashrrev_i32_e32 v19, 31, v18
	v_and_b32_e32 v20, 56, v14
	v_lshlrev_b64 v[16:17], 13, v[18:19]
	v_lshl_add_u64 v[2:3], s[24:25], 0, v[16:17]
	v_lshlrev_b32_e32 v0, 1, v20
	v_add_u32_e32 v22, 0x200, v12
	v_lshl_add_u64 v[8:9], v[2:3], 0, v[0:1]
	v_mov_b32_e32 v2, v1
	v_mov_b32_e32 v3, v1
	v_mov_b32_e32 v0, v1
	v_lshlrev_b32_e32 v198, 3, v22
	v_mov_b64_e32 v[194:195], v[2:3]
	v_ashrrev_i32_e32 v199, 31, v198
	v_mov_b64_e32 v[192:193], v[0:1]
	s_and_saveexec_b64 s[44:45], s[0:1]
	s_cbranch_execz .LBB0_957
	global_load_dwordx4 v[192:195], v[8:9], off
	v_lshl_add_u64 v[8:9], v[198:199], 1, s[42:43]

.LBB0_959:
	s_or_b64 exec, exec, s[44:45]
	s_and_b32 s6, s26, 56
	v_mad_u64_u32 v[2:3], s[24:25], v18, s48, v[20:21]
	v_lshl_add_u32 v215, v2, 1, 0
	v_lshlrev_b32_e32 v2, 1, v209
	v_lshrrev_b32_e32 v3, 1, v12
	s_add_i32 s24, s53, s6
	v_and_b32_e32 v0, 19, v12
	v_and_b32_e32 v2, 8, v2
	v_and_b32_e32 v3, 4, v3
	s_ashr_i32 s25, s24, 31
	v_or3_b32 v0, v3, v0, v2
	v_lshl_add_u32 v2, v208, 4, 0
	s_lshl_b64 s[44:45], s[24:25], 19
	s_mul_hi_i32 s6, s24, 0xc0000
	s_mul_i32 s24, s24, 0xc0000
	v_mad_u32_u24 v212, v0, s39, v2
	v_and_b32_e32 v0, 7, v12
	s_add_u32 s24, s28, s24
	v_mad_u32_u24 v210, v209, s49, v2
	v_lshl_add_u64 v[2:3], s[44:45], 0, v[16:17]
	v_lshlrev_b32_e32 v0, 4, v0
	s_addc_u32 s25, s29, s6
	v_lshl_add_u64 v[2:3], v[2:3], 0, v[0:1]
	v_lshl_add_u64 v[202:203], v[14:15], 1, s[24:25]
	v_mov_b32_e32 v14, v1
	v_mov_b32_e32 v15, v1
	s_waitcnt vmcnt(0)
	ds_write_b128 v215, v[8:11] offset:26624
	v_lshl_add_u64 v[200:201], s[4:5], 0, v[2:3]
	v_mov_b32_e32 v0, v1
	v_mov_b32_e32 v2, v1
	v_mov_b32_e32 v3, v1
	v_mov_b32_e32 v4, v1
	v_mov_b32_e32 v5, v1
	v_mov_b32_e32 v6, v1
	v_mov_b32_e32 v7, v1
	v_mov_b32_e32 v8, v1
	v_mov_b32_e32 v9, v1
	v_mov_b32_e32 v10, v1
	v_mov_b32_e32 v11, v1
	v_mov_b32_e32 v12, v1
	v_mov_b32_e32 v13, v1
	v_mov_b64_e32 v[30:31], v[14:15]
	v_mov_b64_e32 v[46:47], v[14:15]
	v_mov_b64_e32 v[62:63], v[14:15]
	v_mov_b64_e32 v[78:79], v[14:15]
	v_lshlrev_b32_e32 v207, 3, v208
	s_mov_b32 s24, 0
	v_mov_b32_e32 v206, 0
	v_mov_b32_e32 v211, 0xf149f2ca
	v_mov_b64_e32 v[28:29], v[12:13]
	v_mov_b64_e32 v[26:27], v[10:11]
	v_mov_b64_e32 v[24:25], v[8:9]
	v_mov_b64_e32 v[22:23], v[6:7]
	v_mov_b64_e32 v[20:21], v[4:5]
	v_mov_b64_e32 v[18:19], v[2:3]
	v_mov_b64_e32 v[16:17], v[0:1]
	v_mov_b64_e32 v[44:45], v[12:13]
	v_mov_b64_e32 v[42:43], v[10:11]
	v_mov_b64_e32 v[40:41], v[8:9]
	v_mov_b64_e32 v[38:39], v[6:7]
	v_mov_b64_e32 v[36:37], v[4:5]
	v_mov_b64_e32 v[34:35], v[2:3]
	v_mov_b64_e32 v[32:33], v[0:1]
	v_mov_b64_e32 v[60:61], v[12:13]
	v_mov_b64_e32 v[58:59], v[10:11]
	v_mov_b64_e32 v[56:57], v[8:9]
	v_mov_b64_e32 v[54:55], v[6:7]
	v_mov_b64_e32 v[52:53], v[4:5]
	v_mov_b64_e32 v[50:51], v[2:3]
	v_mov_b64_e32 v[48:49], v[0:1]
	v_mov_b64_e32 v[76:77], v[12:13]
	v_mov_b64_e32 v[74:75], v[10:11]
	v_mov_b64_e32 v[72:73], v[8:9]
	v_mov_b64_e32 v[70:71], v[6:7]
	v_mov_b64_e32 v[68:69], v[4:5]
	v_mov_b64_e32 v[66:67], v[2:3]
	v_mov_b64_e32 v[64:65], v[0:1]
	v_mov_b32_e32 v10, 0xf149f2ca
	v_mov_b32_e32 v0, 0
	s_waitcnt lgkmcnt(0)
	s_barrier
	s_cmp_lg_u32 s99, 0
	s_cbranch_scc0 .Lf_entry

.Lf_entry:
	v_mov_b32_e32 v10, 0
	v_mov_b32_e32 v211, 0

.Lf_962:
	s_or_b64 exec, exec, s[44:45]
	s_and_b32 s6, s24, 1
	s_mul_i32 s24, s6, 0x3400
	v_add_u32_e32 v8, s24, v212
	ds_read_b128 v[12:15], v8
	ds_read_b128 v[80:83], v8 offset:32
	ds_read_b128 v[84:87], v8 offset:64
	ds_read_b128 v[88:91], v8 offset:96
	ds_read_b128 v[92:95], v8 offset:128
	ds_read_b128 v[96:99], v8 offset:160
	s_waitcnt lgkmcnt(5)
	v_mfma_f32_32x32x16_bf16 v[128:143], v[12:15], v[188:191], 0
	v_mfma_f32_32x32x16_bf16 v[112:127], v[12:15], v[176:179], 0
	ds_read_b128 v[12:15], v8 offset:6656
	ds_read_b128 v[216:219], v8 offset:6688
	ds_read_b128 v[220:223], v8 offset:6720
	ds_read_b128 v[224:227], v8 offset:6752
	ds_read_b128 v[228:231], v8 offset:6784
	ds_read_b128 v[232:235], v8 offset:6816
	global_load_dwordx4 v[6:9], v[6:7], off
	s_waitcnt lgkmcnt(10)
	v_mfma_f32_32x32x16_bf16 v[128:143], v[80:83], v[184:187], v[128:143]
	v_mfma_f32_32x32x16_bf16 v[112:127], v[80:83], v[168:171], v[112:127]
	s_waitcnt lgkmcnt(9)
	v_mfma_f32_32x32x16_bf16 v[128:143], v[84:87], v[180:183], v[128:143]
	v_mfma_f32_32x32x16_bf16 v[112:127], v[84:87], v[164:167], v[112:127]
	s_waitcnt lgkmcnt(8)
	v_mfma_f32_32x32x16_bf16 v[128:143], v[88:91], v[172:175], v[128:143]
	v_mfma_f32_32x32x16_bf16 v[112:127], v[88:91], v[152:155], v[112:127]
	s_waitcnt lgkmcnt(7)
	v_mfma_f32_32x32x16_bf16 v[128:143], v[92:95], v[160:163], v[128:143]
	v_mfma_f32_32x32x16_bf16 v[112:127], v[92:95], v[148:151], v[112:127]
	s_waitcnt lgkmcnt(6)
	v_mfma_f32_32x32x16_bf16 v[128:143], v[96:99], v[156:159], v[128:143]
	v_mfma_f32_32x32x16_bf16 v[112:127], v[96:99], v[144:147], v[112:127]
	s_waitcnt lgkmcnt(5)
	v_mfma_f32_32x32x16_bf16 v[96:111], v[12:15], v[188:191], 0
	s_waitcnt lgkmcnt(4)
	v_mfma_f32_32x32x16_bf16 v[96:111], v[216:219], v[184:187], v[96:111]
	v_mfma_f32_32x32x16_bf16 v[80:95], v[12:15], v[176:179], 0
	s_waitcnt lgkmcnt(3)
	v_mfma_f32_32x32x16_bf16 v[96:111], v[220:223], v[180:183], v[96:111]
	v_mfma_f32_32x32x16_bf16 v[80:95], v[216:219], v[168:171], v[80:95]
	s_waitcnt lgkmcnt(2)
	v_mfma_f32_32x32x16_bf16 v[96:111], v[224:227], v[172:175], v[96:111]
	v_mfma_f32_32x32x16_bf16 v[80:95], v[220:223], v[164:167], v[80:95]
	s_waitcnt lgkmcnt(1)
	v_mfma_f32_32x32x16_bf16 v[96:111], v[228:231], v[160:163], v[96:111]
	v_mfma_f32_32x32x16_bf16 v[80:95], v[224:227], v[152:155], v[80:95]
	s_waitcnt lgkmcnt(0)
	v_mfma_f32_32x32x16_bf16 v[96:111], v[232:235], v[156:159], v[96:111]
	v_mfma_f32_32x32x16_bf16 v[80:95], v[228:231], v[148:151], v[80:95]
	v_mfma_f32_32x32x16_bf16 v[80:95], v[232:235], v[144:147], v[80:95]
	s_mul_i32 s24, s6, 0x2400
	v_add_u32_e32 v236, s24, v210
	v_exp_f32_e32 v11, v128
	v_exp_f32_e32 v12, v129
	v_exp_f32_e32 v13, v130
	v_exp_f32_e32 v14, v131
	v_exp_f32_e32 v15, v132
	v_exp_f32_e32 v128, v133
	v_exp_f32_e32 v129, v134
	v_exp_f32_e32 v130, v135
	v_exp_f32_e32 v131, v136
	v_exp_f32_e32 v132, v137
	v_exp_f32_e32 v133, v138
	v_exp_f32_e32 v135, v140
	v_exp_f32_e32 v136, v141
	v_exp_f32_e32 v137, v142
	v_exp_f32_e32 v138, v143
	v_exp_f32_e32 v112, v112
	v_exp_f32_e32 v113, v113
	v_exp_f32_e32 v114, v114
	v_exp_f32_e32 v115, v115
	v_exp_f32_e32 v116, v116
	v_exp_f32_e32 v117, v117
	v_exp_f32_e32 v118, v118
	v_exp_f32_e32 v119, v119
	v_cvt_pk_bf16_f32 v140, v11, v12
	v_cvt_pk_bf16_f32 v141, v13, v14
	v_cvt_pk_bf16_f32 v142, v15, v128
	v_cvt_pk_bf16_f32 v143, v129, v130
	v_cvt_pk_bf16_f32 v216, v112, v113
	v_cvt_pk_bf16_f32 v217, v114, v115
	v_cvt_pk_bf16_f32 v218, v116, v117
	v_cvt_pk_bf16_f32 v219, v118, v119
	ds_read_b128 v[220:223], v236 offset:26624
	ds_read_b128 v[224:227], v236 offset:31232
	v_exp_f32_e32 v134, v139
	v_exp_f32_e32 v120, v120
	s_waitcnt lgkmcnt(1)
	v_mfma_f32_32x32x16_bf16 v[64:79], v[220:223], v[140:143], v[64:79]
	v_exp_f32_e32 v121, v121
	v_exp_f32_e32 v122, v122
	v_exp_f32_e32 v123, v123
	v_exp_f32_e32 v124, v124
	v_exp_f32_e32 v125, v125
	v_exp_f32_e32 v126, v126
	v_exp_f32_e32 v127, v127
	v_mfma_f32_32x32x16_bf16 v[32:47], v[220:223], v[216:219], v[32:47]
	v_cvt_pk_bf16_f32 v220, v131, v132
	v_cvt_pk_bf16_f32 v221, v133, v134
	v_cvt_pk_bf16_f32 v222, v135, v136
	v_cvt_pk_bf16_f32 v223, v137, v138
	v_cvt_pk_bf16_f32 v228, v120, v121
	v_cvt_pk_bf16_f32 v229, v122, v123
	v_cvt_pk_bf16_f32 v230, v124, v125
	v_cvt_pk_bf16_f32 v231, v126, v127
	ds_read_b128 v[232:235], v236 offset:26656
	s_waitcnt lgkmcnt(1)
	v_mfma_f32_32x32x16_bf16 v[16:31], v[224:227], v[216:219], v[16:31]
	ds_read_b128 v[216:219], v236 offset:31264
	v_exp_f32_e32 v237, v106
	v_exp_f32_e32 v106, v81
	v_exp_f32_e32 v139, v82
	v_mfma_f32_32x32x16_bf16 v[48:63], v[224:227], v[140:143], v[48:63]
	v_exp_f32_e32 v140, v83
	v_exp_f32_e32 v141, v84
	v_exp_f32_e32 v142, v85
	v_exp_f32_e32 v143, v86
	v_exp_f32_e32 v96, v96
	v_exp_f32_e32 v97, v97
	v_exp_f32_e32 v98, v98
	v_exp_f32_e32 v99, v99
	v_exp_f32_e32 v100, v100
	v_exp_f32_e32 v101, v101
	v_exp_f32_e32 v102, v102
	v_exp_f32_e32 v103, v103
	v_exp_f32_e32 v80, v80
	s_waitcnt lgkmcnt(1)
	v_mfma_f32_32x32x16_bf16 v[64:79], v[232:235], v[220:223], v[64:79]
	v_exp_f32_e32 v87, v87
	v_mfma_f32_32x32x16_bf16 v[32:47], v[232:235], v[228:231], v[32:47]
	s_waitcnt lgkmcnt(0)
	v_mfma_f32_32x32x16_bf16 v[48:63], v[216:219], v[220:223], v[48:63]
	v_cvt_pk_bf16_f32 v220, v96, v97
	v_cvt_pk_bf16_f32 v221, v98, v99
	v_cvt_pk_bf16_f32 v222, v100, v101
	v_cvt_pk_bf16_f32 v223, v102, v103
	v_cvt_pk_bf16_f32 v224, v80, v106
	v_cvt_pk_bf16_f32 v225, v139, v140
	v_cvt_pk_bf16_f32 v226, v141, v142
	v_cvt_pk_bf16_f32 v227, v143, v87
	ds_read_b128 v[232:235], v236 offset:26688
	v_mfma_f32_32x32x16_bf16 v[16:31], v[216:219], v[228:231], v[16:31]
	ds_read_b128 v[216:219], v236 offset:31296
	v_exp_f32_e32 v104, v104
	v_exp_f32_e32 v105, v105
	v_exp_f32_e32 v82, v107
	s_waitcnt lgkmcnt(1)
	v_mfma_f32_32x32x16_bf16 v[64:79], v[232:235], v[220:223], v[64:79]
	v_exp_f32_e32 v83, v108
	v_exp_f32_e32 v84, v109
	v_exp_f32_e32 v85, v110
	v_exp_f32_e32 v86, v111
	v_exp_f32_e32 v88, v88
	v_exp_f32_e32 v89, v89
	v_exp_f32_e32 v90, v90
	v_mfma_f32_32x32x16_bf16 v[32:47], v[232:235], v[224:227], v[32:47]
	v_exp_f32_e32 v91, v91
	v_exp_f32_e32 v92, v92
	v_exp_f32_e32 v93, v93
	v_exp_f32_e32 v94, v94
	v_exp_f32_e32 v95, v95
	v_cvt_pk_bf16_f32 v108, v104, v105
	v_cvt_pk_bf16_f32 v109, v237, v82
	s_waitcnt lgkmcnt(0)
	v_mfma_f32_32x32x16_bf16 v[48:63], v[216:219], v[220:223], v[48:63]
	v_cvt_pk_bf16_f32 v110, v83, v84
	v_cvt_pk_bf16_f32 v111, v85, v86
	s_xor_b32 s6, s6, 1
	s_mul_i32 s24, s6, 0x3400
	s_add_i32 s24, s24, 0
	v_add_u32_e32 v107, s24, v213
	v_mfma_f32_32x32x16_bf16 v[16:31], v[216:219], v[224:227], v[16:31]
	v_cvt_pk_bf16_f32 v216, v88, v89
	v_cvt_pk_bf16_f32 v217, v90, v91
	v_cvt_pk_bf16_f32 v218, v92, v93
	v_cvt_pk_bf16_f32 v219, v94, v95
	ds_read_b128 v[220:223], v236 offset:26720
	ds_read_b128 v[224:227], v236 offset:31328
	s_waitcnt vmcnt(1)
	ds_write_b128 v107, v[2:5]
	s_waitcnt lgkmcnt(2)
	v_mfma_f32_32x32x16_bf16 v[64:79], v[220:223], v[108:111], v[64:79]
	v_mfma_f32_32x32x16_bf16 v[32:47], v[220:223], v[216:219], v[32:47]
	s_waitcnt lgkmcnt(1)
	v_mfma_f32_32x32x16_bf16 v[48:63], v[224:227], v[108:111], v[48:63]
	v_mfma_f32_32x32x16_bf16 v[16:31], v[224:227], v[216:219], v[16:31]
	s_and_saveexec_b64 s[44:45], s[0:1]
	s_cbranch_execz .Lf_966
	v_add_u32_e32 v2, s24, v214
	s_waitcnt vmcnt(0)
	ds_write_b128 v2, v[6:9]
	v_mov_b64_e32 v[6:7], v[192:193]
	v_mov_b64_e32 v[8:9], v[194:195]
.Lf_966:
	s_or_b64 exec, exec, s[44:45]
	v_add_f32_e32 v2, 0, v112
	v_add_f32_e32 v2, v113, v2
	v_add_f32_e32 v2, v114, v2
	v_add_f32_e32 v2, v115, v2
	v_add_f32_e32 v2, v116, v2
	v_add_f32_e32 v2, v117, v2
	v_add_f32_e32 v2, v118, v2
	v_add_f32_e32 v2, v119, v2
	v_add_f32_e32 v2, v120, v2
	v_add_f32_e32 v2, v121, v2
	v_add_f32_e32 v2, v122, v2
	v_add_f32_e32 v2, v123, v2
	v_add_f32_e32 v2, v124, v2
	v_add_f32_e32 v2, v125, v2
	v_add_f32_e32 v2, v126, v2
	v_add_f32_e32 v2, v127, v2
	v_add_f32_e32 v2, v80, v2
	v_add_f32_e32 v2, v106, v2
	v_add_f32_e32 v2, v139, v2
	v_add_f32_e32 v2, v140, v2
	v_add_f32_e32 v2, v141, v2
	v_add_f32_e32 v2, v142, v2
	v_add_f32_e32 v2, v143, v2
	v_add_f32_e32 v2, v87, v2
	v_add_f32_e32 v2, v88, v2
	v_add_f32_e32 v2, v89, v2
	v_add_f32_e32 v2, v90, v2
	v_add_f32_e32 v2, v91, v2
	v_add_f32_e32 v2, v92, v2
	v_add_f32_e32 v2, v93, v2
	v_add_f32_e32 v2, v94, v2
	v_add_f32_e32 v2, v95, v2
	v_add_f32_e32 v206, v206, v2
	v_add_f32_e32 v2, 0, v11
	v_add_f32_e32 v2, v12, v2
	v_add_f32_e32 v2, v13, v2
	v_add_f32_e32 v2, v14, v2
	v_add_f32_e32 v2, v15, v2
	v_add_f32_e32 v2, v128, v2
	v_add_f32_e32 v2, v129, v2
	v_add_f32_e32 v2, v130, v2
	v_add_f32_e32 v2, v131, v2
	v_add_f32_e32 v2, v132, v2
	v_add_f32_e32 v2, v133, v2
	v_add_f32_e32 v2, v134, v2
	v_add_f32_e32 v2, v135, v2
	v_add_f32_e32 v2, v136, v2
	v_add_f32_e32 v2, v137, v2
	v_add_f32_e32 v2, v138, v2
	v_add_f32_e32 v2, v96, v2
	v_add_f32_e32 v2, v97, v2
	v_add_f32_e32 v2, v98, v2
	v_add_f32_e32 v2, v99, v2
	v_add_f32_e32 v2, v100, v2
	v_add_f32_e32 v2, v101, v2
	v_add_f32_e32 v2, v102, v2
	v_add_f32_e32 v2, v103, v2
	v_add_f32_e32 v2, v104, v2
	v_add_f32_e32 v2, v105, v2
	v_add_f32_e32 v2, v237, v2
	v_add_f32_e32 v2, v82, v2
	v_add_f32_e32 v2, v83, v2
	v_add_f32_e32 v2, v84, v2
	v_add_f32_e32 v2, v85, v2
	s_mulk_i32 s6, 0x2400
	v_add_f32_e32 v2, v86, v2
	v_add_f32_e32 v0, v0, v2
	v_add_u32_e32 v2, s6, v215
	v_lshl_add_u64 v[200:201], v[200:201], 0, s[10:11]
	s_cmp_eq_u32 s33, 63
	v_lshl_add_u64 v[202:203], v[202:203], 0, s[12:13]
	s_waitcnt vmcnt(0)
	ds_write_b128 v2, v[6:9] offset:26624
	s_waitcnt lgkmcnt(0)
	s_barrier
	s_cbranch_scc1 .LBB0_970
	s_mov_b32 s24, s33
	s_branch .Lf_960

.LBB0_972:
	v_sub_f32_e32 v2, v128, v10
	v_exp_f32_e32 v2, v2
	v_sub_f32_e32 v3, v129, v10
	v_exp_f32_e32 v3, v3
	v_sub_f32_e32 v4, v130, v10
	v_exp_f32_e32 v4, v4
	v_sub_f32_e32 v5, v131, v10
	v_exp_f32_e32 v5, v5
	v_sub_f32_e32 v7, v132, v10
	v_add_f32_e32 v6, 0, v2
	v_exp_f32_e32 v7, v7
	v_sub_f32_e32 v8, v133, v10
	v_add_f32_e32 v6, v3, v6
	v_exp_f32_e32 v8, v8
	v_sub_f32_e32 v9, v134, v10
	v_add_f32_e32 v6, v4, v6
	v_exp_f32_e32 v9, v9
	v_sub_f32_e32 v11, v135, v10
	v_add_f32_e32 v6, v5, v6
	v_exp_f32_e32 v11, v11
	v_add_f32_e32 v6, v7, v6
	v_add_f32_e32 v6, v8, v6
	v_add_f32_e32 v6, v9, v6
	v_add_f32_e32 v128, v11, v6
	v_sub_f32_e32 v6, v136, v10
	v_exp_f32_e32 v129, v6
	v_sub_f32_e32 v6, v137, v10
	v_exp_f32_e32 v130, v6
	v_sub_f32_e32 v6, v138, v10
	v_exp_f32_e32 v131, v6
	v_sub_f32_e32 v6, v139, v10
	v_exp_f32_e32 v132, v6
	v_sub_f32_e32 v6, v140, v10
	v_exp_f32_e32 v133, v6
	v_sub_f32_e32 v6, v141, v10
	v_exp_f32_e32 v134, v6
	v_sub_f32_e32 v6, v142, v10
	v_exp_f32_e32 v135, v6
	v_sub_f32_e32 v6, v143, v10
	v_exp_f32_e32 v136, v6
	v_sub_f32_e32 v6, v96, v10
	v_exp_f32_e32 v137, v6
	v_sub_f32_e32 v6, v97, v10
	v_exp_f32_e32 v138, v6
	v_sub_f32_e32 v6, v98, v10
	v_exp_f32_e32 v139, v6
	v_sub_f32_e32 v6, v99, v10
	v_exp_f32_e32 v140, v6
	v_sub_f32_e32 v6, v100, v10
	v_exp_f32_e32 v141, v6
	v_sub_f32_e32 v6, v101, v10
	v_exp_f32_e32 v142, v6
	v_sub_f32_e32 v6, v102, v10
	v_exp_f32_e32 v143, v6
	v_sub_f32_e32 v6, v103, v10
	v_exp_f32_e32 v144, v6
	v_sub_f32_e32 v6, v104, v10
	v_exp_f32_e32 v145, v6
	v_sub_f32_e32 v6, v112, v211
	v_exp_f32_e32 v96, v6
	v_sub_f32_e32 v6, v113, v211
	v_exp_f32_e32 v97, v6
	v_sub_f32_e32 v6, v114, v211
	v_exp_f32_e32 v98, v6
	v_sub_f32_e32 v6, v115, v211
	v_exp_f32_e32 v99, v6
	v_sub_f32_e32 v6, v116, v211
	v_exp_f32_e32 v100, v6
	v_sub_f32_e32 v6, v117, v211
	v_exp_f32_e32 v101, v6
	v_sub_f32_e32 v6, v118, v211
	v_exp_f32_e32 v102, v6
	v_sub_f32_e32 v6, v119, v211
	v_exp_f32_e32 v103, v6
	v_cvt_pk_bf16_f32 v2, v2, v3
	v_cvt_pk_bf16_f32 v3, v4, v5
	v_cvt_pk_bf16_f32 v4, v7, v8
	v_cvt_pk_bf16_f32 v5, v9, v11
	v_cvt_pk_bf16_f32 v6, v96, v97
	v_cvt_pk_bf16_f32 v7, v98, v99
	v_cvt_pk_bf16_f32 v8, v100, v101
	v_cvt_pk_bf16_f32 v9, v102, v103
	ds_read_b128 v[12:15], v210 offset:35840
	ds_read_b128 v[116:119], v210 offset:40448
	v_sub_f32_e32 v11, v106, v10
	v_exp_f32_e32 v147, v11
	v_sub_f32_e32 v11, v107, v10
	v_sub_f32_e32 v104, v105, v10
	v_exp_f32_e32 v148, v11
	v_sub_f32_e32 v11, v120, v211
	v_exp_f32_e32 v146, v104
	v_exp_f32_e32 v104, v11
	v_sub_f32_e32 v11, v121, v211
	v_exp_f32_e32 v105, v11
	v_sub_f32_e32 v11, v122, v211
	v_exp_f32_e32 v106, v11
	v_sub_f32_e32 v11, v123, v211
	v_exp_f32_e32 v107, v11
	v_sub_f32_e32 v11, v124, v211
	s_waitcnt lgkmcnt(1)
	v_mfma_f32_32x32x16_bf16 v[32:47], v[12:15], v[6:9], v[32:47]
	v_exp_f32_e32 v112, v11
	v_sub_f32_e32 v11, v125, v211
	v_exp_f32_e32 v113, v11
	v_sub_f32_e32 v11, v126, v211
	v_exp_f32_e32 v114, v11
	v_sub_f32_e32 v11, v127, v211
	v_exp_f32_e32 v115, v11
	s_waitcnt lgkmcnt(0)
	v_mfma_f32_32x32x16_bf16 v[16:31], v[116:119], v[6:9], v[16:31]
	v_sub_f32_e32 v6, v108, v10
	v_exp_f32_e32 v124, v6
	v_sub_f32_e32 v6, v109, v10
	v_exp_f32_e32 v125, v6
	v_sub_f32_e32 v6, v80, v211
	v_exp_f32_e32 v108, v6
	v_sub_f32_e32 v11, v81, v211
	v_mfma_f32_32x32x16_bf16 v[64:79], v[12:15], v[2:5], v[64:79]
	v_exp_f32_e32 v109, v11
	v_sub_f32_e32 v11, v82, v211
	v_exp_f32_e32 v80, v11
	v_sub_f32_e32 v11, v83, v211
	v_exp_f32_e32 v81, v11
	v_sub_f32_e32 v11, v84, v211
	v_exp_f32_e32 v82, v11
	v_mfma_f32_32x32x16_bf16 v[48:63], v[116:119], v[2:5], v[48:63]
	v_cvt_pk_bf16_f32 v2, v129, v130
	v_cvt_pk_bf16_f32 v3, v131, v132
	v_cvt_pk_bf16_f32 v4, v133, v134
	v_cvt_pk_bf16_f32 v5, v135, v136
	v_cvt_pk_bf16_f32 v12, v104, v105
	v_cvt_pk_bf16_f32 v13, v106, v107
	v_cvt_pk_bf16_f32 v14, v112, v113
	v_cvt_pk_bf16_f32 v15, v114, v115
	ds_read_b128 v[120:123], v210 offset:35872
	ds_read_b128 v[6:9], v210 offset:40480
	v_sub_f32_e32 v11, v85, v211
	s_waitcnt lgkmcnt(0)
	v_mfma_f32_32x32x16_bf16 v[48:63], v[6:9], v[2:5], v[48:63]
	v_exp_f32_e32 v83, v11
	v_sub_f32_e32 v11, v86, v211
	v_exp_f32_e32 v84, v11
	v_sub_f32_e32 v11, v87, v211
	v_exp_f32_e32 v85, v11
	s_ashr_i32 s0, s40, 3
	s_and_b32 s33, s53, 7
	v_mfma_f32_32x32x16_bf16 v[16:31], v[6:9], v[12:15], v[16:31]
	v_sub_f32_e32 v6, v110, v10
	s_ashr_i32 s1, s0, 31
	s_lshl_b64 s[0:1], s[0:1], 12
	s_lshl_b32 s6, s33, 2
	s_add_u32 s40, s8, s6
	s_addc_u32 s41, s9, 0
	v_mfma_f32_32x32x16_bf16 v[32:47], v[120:123], v[12:15], v[32:47]
	v_exp_f32_e32 v14, v6
	v_sub_f32_e32 v6, v111, v10
	v_exp_f32_e32 v15, v6
	v_sub_f32_e32 v6, v88, v211
	v_exp_f32_e32 v86, v6
	v_sub_f32_e32 v10, v89, v211
	v_exp_f32_e32 v87, v10
	v_mfma_f32_32x32x16_bf16 v[64:79], v[120:123], v[2:5], v[64:79]
	v_cvt_pk_bf16_f32 v2, v137, v138
	v_cvt_pk_bf16_f32 v3, v139, v140
	v_cvt_pk_bf16_f32 v4, v141, v142
	v_cvt_pk_bf16_f32 v5, v143, v144
	v_cvt_pk_bf16_f32 v116, v108, v109
	v_cvt_pk_bf16_f32 v117, v80, v81
	v_cvt_pk_bf16_f32 v118, v82, v83
	v_cvt_pk_bf16_f32 v119, v84, v85
	ds_read_b128 v[120:123], v210 offset:35904
	ds_read_b128 v[6:9], v210 offset:40512
	s_waitcnt lgkmcnt(0)
	v_mfma_f32_32x32x16_bf16 v[48:63], v[6:9], v[2:5], v[48:63]
	v_sub_f32_e32 v10, v90, v211
	v_exp_f32_e32 v88, v10
	v_sub_f32_e32 v10, v91, v211
	v_exp_f32_e32 v89, v10
	v_sub_f32_e32 v10, v92, v211
	v_exp_f32_e32 v90, v10
	v_sub_f32_e32 v10, v93, v211
	v_mfma_f32_32x32x16_bf16 v[16:31], v[6:9], v[116:119], v[16:31]
	v_add_f32_e32 v6, v129, v128
	v_add_f32_e32 v6, v130, v6
	v_add_f32_e32 v6, v131, v6
	v_add_f32_e32 v6, v132, v6
	v_add_f32_e32 v6, v133, v6
	v_exp_f32_e32 v91, v10
	v_sub_f32_e32 v10, v94, v211
	v_add_f32_e32 v94, v134, v6
	v_add_f32_e32 v94, v135, v94
	v_add_f32_e32 v94, v136, v94
	v_add_f32_e32 v94, v137, v94
	v_add_f32_e32 v94, v138, v94
	v_exp_f32_e32 v92, v10
	v_sub_f32_e32 v10, v95, v211
	v_add_f32_e32 v94, v139, v94
	v_mfma_f32_32x32x16_bf16 v[64:79], v[120:123], v[2:5], v[64:79]
	v_exp_f32_e32 v93, v10
	v_cvt_pk_bf16_f32 v2, v145, v146
	v_cvt_pk_bf16_f32 v3, v147, v148
	v_cvt_pk_bf16_f32 v4, v124, v125
	v_cvt_pk_bf16_f32 v5, v14, v15
	v_cvt_pk_bf16_f32 v10, v86, v87
	v_cvt_pk_bf16_f32 v11, v88, v89
	v_mfma_f32_32x32x16_bf16 v[32:47], v[120:123], v[116:119], v[32:47]
	v_cvt_pk_bf16_f32 v12, v90, v91
	v_cvt_pk_bf16_f32 v13, v92, v93
	ds_read_b128 v[120:123], v210 offset:35936
	ds_read_b128 v[6:9], v210 offset:40544
	v_add_f32_e32 v94, v140, v94
	v_add_f32_e32 v94, v141, v94
	v_add_f32_e32 v94, v142, v94
	v_add_f32_e32 v94, v143, v94
	v_add_f32_e32 v94, v144, v94
	v_add_f32_e32 v94, v145, v94
	v_add_f32_e32 v94, v146, v94
	v_add_f32_e32 v94, v147, v94
	v_add_f32_e32 v94, v148, v94
	s_waitcnt lgkmcnt(1)
	v_mfma_f32_32x32x16_bf16 v[64:79], v[120:123], v[2:5], v[64:79]
	s_waitcnt lgkmcnt(0)
	s_barrier
	v_mfma_f32_32x32x16_bf16 v[48:63], v[6:9], v[2:5], v[48:63]
	v_add_f32_e32 v2, v124, v94
	v_add_f32_e32 v2, v125, v2
	v_add_f32_e32 v2, v14, v2
	v_add_f32_e32 v2, v15, v2
	v_add_f32_e32 v0, v0, v2
	v_mov_b32_e32 v4, v0
	s_nop 1
	v_permlane32_swap_b32_e32 v0, v4
	v_add_f32_e32 v0, v0, v4
	v_min_u32_e32 v242, v242, v0
	v_max_u32_e32 v243, v243, v0
	v_div_scale_f32 v4, s[24:25], v0, v0, 1.0
	v_rcp_f32_e32 v5, v4
	v_mfma_f32_32x32x16_bf16 v[16:31], v[6:9], v[10:13], v[16:31]
	v_lshl_add_u64 v[2:3], s[0:1], 0, v[196:197]
	v_or_b32_e32 v2, v2, v209
	v_fma_f32 v6, -v4, v5, 1.0
	v_fmac_f32_e32 v5, v6, v5
	v_div_scale_f32 v6, vcc, 1.0, v0, 1.0
	v_mul_f32_e32 v7, v6, v5
	v_fma_f32 v8, -v4, v7, v6
	v_fmac_f32_e32 v7, v8, v5
	v_fma_f32 v4, -v4, v7, v6
	v_div_fmas_f32 v4, v4, v5, v7
	v_mfma_f32_32x32x16_bf16 v[32:47], v[120:123], v[10:13], v[32:47]
	v_div_fixup_f32 v12, v4, v0, 1.0
	v_mul_f32_e64 v64, v64, v12
	v_mul_f32_e64 v65, v65, v12
	v_mul_f32_e64 v66, v66, v12
	v_mul_f32_e64 v67, v67, v12
	v_mul_f32_e32 v0, v65, v65
	v_fmac_f32_e32 v0, v64, v64
	v_fmac_f32_e32 v0, v66, v66
	v_pk_mul_f32 v[68:69], v[68:69], v[12:13] op_sel_hi:[1,0]
	v_fmac_f32_e32 v0, v67, v67
	v_fmac_f32_e32 v0, v68, v68
	v_pk_mul_f32 v[70:71], v[70:71], v[12:13] op_sel_hi:[1,0]
	v_fmac_f32_e32 v0, v69, v69
	v_fmac_f32_e32 v0, v70, v70
	v_pk_mul_f32 v[72:73], v[72:73], v[12:13] op_sel_hi:[1,0]
	v_fmac_f32_e32 v0, v71, v71
	v_fmac_f32_e32 v0, v72, v72
	v_pk_mul_f32 v[74:75], v[74:75], v[12:13] op_sel_hi:[1,0]
	v_fmac_f32_e32 v0, v73, v73
	v_fmac_f32_e32 v0, v74, v74
	v_pk_mul_f32 v[76:77], v[76:77], v[12:13] op_sel_hi:[1,0]
	v_fmac_f32_e32 v0, v75, v75
	v_fmac_f32_e32 v0, v76, v76
	v_pk_mul_f32 v[78:79], v[78:79], v[12:13] op_sel_hi:[1,0]
	v_fmac_f32_e32 v0, v77, v77
	v_fmac_f32_e32 v0, v78, v78
	v_fmac_f32_e32 v0, v79, v79
	v_pk_mul_f32 v[14:15], v[54:55], v[12:13] op_sel_hi:[1,0]
	v_pk_mul_f32 v[54:55], v[48:49], v[12:13] op_sel_hi:[1,0]
	v_pk_mul_f32 v[50:51], v[50:51], v[12:13] op_sel_hi:[1,0]
	v_fmac_f32_e32 v0, v54, v54
	v_fmac_f32_e32 v0, v55, v55
	v_fmac_f32_e32 v0, v50, v50
	v_pk_mul_f32 v[52:53], v[52:53], v[12:13] op_sel_hi:[1,0]
	v_fmac_f32_e32 v0, v51, v51
	v_fmac_f32_e32 v0, v52, v52
	v_fmac_f32_e32 v0, v53, v53
	v_fmac_f32_e32 v0, v14, v14
	v_pk_mul_f32 v[10:11], v[56:57], v[12:13] op_sel_hi:[1,0]
	v_fmac_f32_e32 v0, v15, v15
	v_fmac_f32_e32 v0, v10, v10
	v_pk_mul_f32 v[8:9], v[58:59], v[12:13] op_sel_hi:[1,0]
	v_fmac_f32_e32 v0, v11, v11
	v_fmac_f32_e32 v0, v8, v8
	v_pk_mul_f32 v[6:7], v[60:61], v[12:13] op_sel_hi:[1,0]
	v_fmac_f32_e32 v0, v9, v9
	v_fmac_f32_e32 v0, v6, v6
	v_pk_mul_f32 v[4:5], v[62:63], v[12:13] op_sel_hi:[1,0]
	v_fmac_f32_e32 v0, v7, v7
	v_fmac_f32_e32 v0, v4, v4
	v_fmac_f32_e32 v0, v5, v5
	v_mov_b32_e32 v12, v0
	v_cmp_eq_u32_e64 s[0:1], 0, v208
	s_nop 0
	v_permlane32_swap_b32_e32 v0, v12
	s_and_saveexec_b64 s[42:43], s[0:1]
	s_cbranch_execz .LBB0_974
	v_add_f32_e32 v0, v0, v12
	v_lshlrev_b64 v[12:13], 5, v[2:3]
	v_lshl_add_u64 v[12:13], s[40:41], 0, v[12:13]
	global_store_dword v[12:13], v0, off
.LBB0_974:
	s_or_b64 exec, exec, s[42:43]
	v_mov_b64_e32 v[12:13], s[72:73]
	v_mad_u64_u32 v[12:13], s[24:25], v2, s52, v[12:13]
	s_lshl_b32 s6, s33, 7
	v_mad_i32_i24 v13, v3, s52, v13
	v_lshl_add_u64 v[48:49], v[12:13], 0, s[6:7]
	v_lshlrev_b32_e32 v0, 1, v207
	v_lshl_add_u64 v[56:57], v[48:49], 0, v[0:1]
	global_load_dwordx4 v[58:61], v[56:57], off offset:3072
	s_add_u32 s42, s86, s6
	v_lshlrev_b64 v[48:49], 11, v[2:3]
	s_addc_u32 s43, s87, 0
	v_lshl_add_u64 v[48:49], s[42:43], 0, v[48:49]
	v_lshl_add_u64 v[48:49], v[48:49], 0, v[0:1]
	v_or_b32_e32 v2, 32, v2
	s_waitcnt vmcnt(0)
	v_permlane32_swap_b32_e32 v58, v60
	v_permlane32_swap_b32_e32 v59, v61
	v_lshlrev_b32_e32 v62, 16, v58
	v_and_b32_e32 v58, 0xffff0000, v58
	v_lshlrev_b32_e32 v63, 16, v59
	v_and_b32_e32 v59, 0xffff0000, v59
	v_lshlrev_b32_e32 v94, 16, v60
	v_and_b32_e32 v60, 0xffff0000, v60
	v_lshlrev_b32_e32 v95, 16, v61
	v_and_b32_e32 v61, 0xffff0000, v61
	v_mul_f32_e32 v111, 0xbfb8aa3b, v58
	v_mul_f32_e32 v117, 0xbfb8aa3b, v59
	v_mul_f32_e32 v119, 0xbfb8aa3b, v60
	v_mul_f32_e32 v121, 0xbfb8aa3b, v61
	v_mul_f32_e32 v110, 0xbfb8aa3b, v62
	v_mul_f32_e32 v116, 0xbfb8aa3b, v63
	v_mul_f32_e32 v118, 0xbfb8aa3b, v94
	v_mul_f32_e32 v120, 0xbfb8aa3b, v95
	v_exp_f32_e32 v111, v111
	v_exp_f32_e32 v117, v117
	v_exp_f32_e32 v119, v119
	v_exp_f32_e32 v121, v121
	v_exp_f32_e32 v110, v110
	v_exp_f32_e32 v116, v116
	v_exp_f32_e32 v118, v118
	v_exp_f32_e32 v120, v120
	v_add_f32_e32 v111, 1.0, v111
	v_add_f32_e32 v117, 1.0, v117
	v_add_f32_e32 v119, 1.0, v119
	v_add_f32_e32 v121, 1.0, v121
	v_add_f32_e32 v110, 1.0, v110
	v_add_f32_e32 v116, 1.0, v116
	v_add_f32_e32 v118, 1.0, v118
	v_add_f32_e32 v120, 1.0, v120
	v_rcp_f32_e32 v111, v111
	v_rcp_f32_e32 v117, v117
	v_rcp_f32_e32 v119, v119
	v_rcp_f32_e32 v121, v121
	v_rcp_f32_e32 v110, v110
	v_rcp_f32_e32 v116, v116
	v_rcp_f32_e32 v118, v118
	v_rcp_f32_e32 v120, v120
	v_mul_f32_e32 v58, v111, v58
	v_mul_f32_e32 v59, v117, v59
	v_mul_f32_e32 v60, v119, v60
	v_mul_f32_e32 v61, v121, v61
	v_mul_f32_e32 v62, v110, v62
	v_mul_f32_e32 v63, v116, v63
	v_mul_f32_e32 v94, v118, v94
	v_mul_f32_e32 v95, v120, v95
	v_mul_f32_e32 v58, v65, v58
	v_mul_f32_e32 v59, v67, v59
	v_mul_f32_e32 v60, v69, v60
	v_mul_f32_e32 v61, v71, v61
	v_mul_f32_e32 v62, v64, v62
	v_mul_f32_e32 v63, v66, v63
	v_mul_f32_e32 v64, v68, v94
	v_mul_f32_e32 v65, v70, v95
	v_cvt_pk_bf16_f32 v58, v62, v58
	v_cvt_pk_bf16_f32 v59, v63, v59
	v_cvt_pk_bf16_f32 v60, v64, v60
	v_cvt_pk_bf16_f32 v61, v65, v61
	s_nop 0
	v_permlane32_swap_b32_e32 v58, v60
	v_permlane32_swap_b32_e32 v59, v61
	global_store_dwordx4 v[48:49], v[58:61], off
	global_load_dwordx4 v[58:61], v[56:57], off offset:3104
	s_waitcnt vmcnt(0)
	v_permlane32_swap_b32_e32 v58, v60
	v_permlane32_swap_b32_e32 v59, v61
	v_lshlrev_b32_e32 v62, 16, v58
	v_and_b32_e32 v58, 0xffff0000, v58
	v_lshlrev_b32_e32 v63, 16, v59
	v_and_b32_e32 v59, 0xffff0000, v59
	v_lshlrev_b32_e32 v64, 16, v60
	v_and_b32_e32 v60, 0xffff0000, v60
	v_lshlrev_b32_e32 v65, 16, v61
	v_and_b32_e32 v61, 0xffff0000, v61
	v_mul_f32_e32 v67, 0xbfb8aa3b, v58
	v_mul_f32_e32 v69, 0xbfb8aa3b, v59
	v_mul_f32_e32 v71, 0xbfb8aa3b, v60
	v_mul_f32_e32 v95, 0xbfb8aa3b, v61
	v_mul_f32_e32 v66, 0xbfb8aa3b, v62
	v_mul_f32_e32 v68, 0xbfb8aa3b, v63
	v_mul_f32_e32 v70, 0xbfb8aa3b, v64
	v_mul_f32_e32 v94, 0xbfb8aa3b, v65
	v_exp_f32_e32 v67, v67
	v_exp_f32_e32 v69, v69
	v_exp_f32_e32 v71, v71
	v_exp_f32_e32 v95, v95
	v_exp_f32_e32 v66, v66
	v_exp_f32_e32 v68, v68
	v_exp_f32_e32 v70, v70
	v_exp_f32_e32 v94, v94
	v_add_f32_e32 v67, 1.0, v67
	v_add_f32_e32 v69, 1.0, v69
	v_add_f32_e32 v71, 1.0, v71
	v_add_f32_e32 v95, 1.0, v95
	v_add_f32_e32 v66, 1.0, v66
	v_add_f32_e32 v68, 1.0, v68
	v_add_f32_e32 v70, 1.0, v70
	v_add_f32_e32 v94, 1.0, v94
	v_rcp_f32_e32 v67, v67
	v_rcp_f32_e32 v69, v69
	v_rcp_f32_e32 v71, v71
	v_rcp_f32_e32 v95, v95
	v_rcp_f32_e32 v66, v66
	v_rcp_f32_e32 v68, v68
	v_rcp_f32_e32 v70, v70
	v_rcp_f32_e32 v94, v94
	v_mul_f32_e32 v58, v67, v58
	v_mul_f32_e32 v59, v69, v59
	v_mul_f32_e32 v60, v71, v60
	v_mul_f32_e32 v61, v95, v61
	v_mul_f32_e32 v62, v66, v62
	v_mul_f32_e32 v63, v68, v63
	v_mul_f32_e32 v64, v70, v64
	v_mul_f32_e32 v65, v94, v65
	v_mul_f32_e32 v58, v73, v58
	v_mul_f32_e32 v59, v75, v59
	v_mul_f32_e32 v60, v77, v60
	v_mul_f32_e32 v61, v79, v61
	v_mul_f32_e32 v62, v72, v62
	v_mul_f32_e32 v63, v74, v63
	v_mul_f32_e32 v64, v76, v64
	v_mul_f32_e32 v65, v78, v65
	v_cvt_pk_bf16_f32 v58, v62, v58
	v_cvt_pk_bf16_f32 v59, v63, v59
	v_cvt_pk_bf16_f32 v60, v64, v60
	v_cvt_pk_bf16_f32 v61, v65, v61
	v_add_f32_e32 v62, 0, v96
	v_permlane32_swap_b32_e32 v58, v60
	v_permlane32_swap_b32_e32 v59, v61
	global_store_dwordx4 v[48:49], v[58:61], off offset:32
	global_load_dwordx4 v[58:61], v[56:57], off offset:3136
	v_add_f32_e32 v62, v97, v62
	v_add_f32_e32 v62, v98, v62
	v_add_f32_e32 v62, v99, v62
	v_add_f32_e32 v62, v100, v62
	v_add_f32_e32 v62, v101, v62
	v_add_f32_e32 v62, v102, v62
	v_add_f32_e32 v62, v103, v62
	v_add_f32_e32 v62, v104, v62
	v_add_f32_e32 v62, v105, v62
	v_add_f32_e32 v62, v106, v62
	v_add_f32_e32 v62, v107, v62
	v_add_f32_e32 v62, v112, v62
	v_add_f32_e32 v62, v113, v62
	v_add_f32_e32 v62, v114, v62
	v_add_f32_e32 v62, v115, v62
	v_add_f32_e32 v62, v108, v62
	v_add_f32_e32 v62, v109, v62
	s_waitcnt vmcnt(0)
	v_permlane32_swap_b32_e32 v58, v60
	v_permlane32_swap_b32_e32 v59, v61
	v_lshlrev_b32_e32 v64, 16, v59
	v_and_b32_e32 v59, 0xffff0000, v59
	v_lshlrev_b32_e32 v65, 16, v60
	v_and_b32_e32 v60, 0xffff0000, v60
	v_lshlrev_b32_e32 v63, 16, v58
	v_and_b32_e32 v58, 0xffff0000, v58
	v_lshlrev_b32_e32 v66, 16, v61
	v_and_b32_e32 v61, 0xffff0000, v61
	v_mul_f32_e32 v70, 0xbfb8aa3b, v59
	v_mul_f32_e32 v71, 0xbfb8aa3b, v65
	v_mul_f32_e32 v72, 0xbfb8aa3b, v60
	v_mul_f32_e32 v67, 0xbfb8aa3b, v63
	v_mul_f32_e32 v68, 0xbfb8aa3b, v58
	v_mul_f32_e32 v69, 0xbfb8aa3b, v64
	v_mul_f32_e32 v73, 0xbfb8aa3b, v66
	v_mul_f32_e32 v74, 0xbfb8aa3b, v61
	v_exp_f32_e32 v70, v70
	v_exp_f32_e32 v71, v71
	v_exp_f32_e32 v72, v72
	v_exp_f32_e32 v67, v67
	v_exp_f32_e32 v68, v68
	v_exp_f32_e32 v69, v69
	v_exp_f32_e32 v73, v73
	v_exp_f32_e32 v74, v74
	v_add_f32_e32 v70, 1.0, v70
	v_add_f32_e32 v71, 1.0, v71
	v_add_f32_e32 v72, 1.0, v72
	v_add_f32_e32 v67, 1.0, v67
	v_add_f32_e32 v68, 1.0, v68
	v_add_f32_e32 v69, 1.0, v69
	v_add_f32_e32 v73, 1.0, v73
	v_add_f32_e32 v74, 1.0, v74
	v_rcp_f32_e32 v70, v70
	v_rcp_f32_e32 v71, v71
	v_rcp_f32_e32 v72, v72
	v_rcp_f32_e32 v67, v67
	v_rcp_f32_e32 v68, v68
	v_rcp_f32_e32 v69, v69
	v_rcp_f32_e32 v73, v73
	v_rcp_f32_e32 v74, v74
	v_mul_f32_e32 v59, v70, v59
	v_mul_f32_e32 v65, v71, v65
	v_mul_f32_e32 v60, v72, v60
	v_mul_f32_e32 v63, v67, v63
	v_mul_f32_e32 v58, v68, v58
	v_mul_f32_e32 v64, v69, v64
	v_mul_f32_e32 v66, v73, v66
	v_mul_f32_e32 v61, v74, v61
	v_mul_f32_e32 v51, v51, v59
	v_mul_f32_e32 v52, v52, v65
	v_mul_f32_e32 v53, v53, v60
	v_mul_f32_e32 v54, v54, v63
	v_mul_f32_e32 v55, v55, v58
	v_mul_f32_e32 v58, v50, v64
	v_mul_f32_e32 v14, v14, v66
	v_mul_f32_e32 v15, v15, v61
	v_cvt_pk_bf16_f32 v50, v54, v55
	v_cvt_pk_bf16_f32 v51, v58, v51
	v_cvt_pk_bf16_f32 v52, v52, v53
	v_cvt_pk_bf16_f32 v53, v14, v15
	v_add_f32_e32 v14, v80, v62
	v_permlane32_swap_b32_e32 v50, v52
	v_permlane32_swap_b32_e32 v51, v53
	global_store_dwordx4 v[48:49], v[50:53], off offset:64
	global_load_dwordx4 v[50:53], v[56:57], off offset:3168
	v_add_f32_e32 v14, v81, v14
	v_add_f32_e32 v14, v82, v14
	v_add_f32_e32 v14, v83, v14
	v_add_f32_e32 v14, v84, v14
	v_add_f32_e32 v14, v85, v14
	v_add_f32_e32 v14, v86, v14
	v_add_f32_e32 v14, v87, v14
	v_add_f32_e32 v14, v88, v14
	v_add_f32_e32 v14, v89, v14
	v_add_f32_e32 v14, v90, v14
	v_add_f32_e32 v14, v91, v14
	v_add_f32_e32 v14, v92, v14
	v_add_f32_e32 v14, v93, v14
	v_add_f32_e32 v14, v206, v14
	v_mov_b32_e32 v15, v14
	s_nop 1
	v_permlane32_swap_b32_e32 v14, v15
	v_add_f32_e32 v14, v14, v15
	v_min_u32_e32 v242, v242, v14
	v_max_u32_e32 v243, v243, v14
	v_div_scale_f32 v15, s[24:25], v14, v14, 1.0
	v_rcp_f32_e32 v54, v15
	v_div_scale_f32 v55, vcc, 1.0, v14, 1.0
	v_fma_f32 v56, -v15, v54, 1.0
	v_fmac_f32_e32 v54, v56, v54
	v_mul_f32_e32 v56, v55, v54
	v_fma_f32 v57, -v15, v56, v55
	v_fmac_f32_e32 v56, v57, v54
	v_fma_f32 v15, -v15, v56, v55
	v_div_fmas_f32 v15, v15, v54, v56
	v_div_fixup_f32 v54, v15, v14, 1.0
	v_pk_mul_f32 v[32:33], v[32:33], v[54:55] op_sel_hi:[1,0]
	v_pk_mul_f32 v[14:15], v[30:31], v[54:55] op_sel_hi:[1,0]
	v_mul_f32_e32 v30, v33, v33
	v_pk_mul_f32 v[34:35], v[34:35], v[54:55] op_sel_hi:[1,0]
	v_fmac_f32_e32 v30, v32, v32
	v_fmac_f32_e32 v30, v34, v34
	v_pk_mul_f32 v[36:37], v[36:37], v[54:55] op_sel_hi:[1,0]
	v_fmac_f32_e32 v30, v35, v35
	v_fmac_f32_e32 v30, v36, v36
	v_pk_mul_f32 v[38:39], v[38:39], v[54:55] op_sel_hi:[1,0]
	v_fmac_f32_e32 v30, v37, v37
	v_fmac_f32_e32 v30, v38, v38
	v_pk_mul_f32 v[40:41], v[40:41], v[54:55] op_sel_hi:[1,0]
	v_fmac_f32_e32 v30, v39, v39
	v_fmac_f32_e32 v30, v40, v40
	v_pk_mul_f32 v[42:43], v[42:43], v[54:55] op_sel_hi:[1,0]
	v_fmac_f32_e32 v30, v41, v41
	v_fmac_f32_e32 v30, v42, v42
	v_pk_mul_f32 v[44:45], v[44:45], v[54:55] op_sel_hi:[1,0]
	v_fmac_f32_e32 v30, v43, v43
	v_fmac_f32_e32 v30, v44, v44
	v_pk_mul_f32 v[46:47], v[46:47], v[54:55] op_sel_hi:[1,0]
	v_fmac_f32_e32 v30, v45, v45
	v_fmac_f32_e32 v30, v46, v46
	v_pk_mul_f32 v[16:17], v[16:17], v[54:55] op_sel_hi:[1,0]
	v_fmac_f32_e32 v30, v47, v47
	v_fmac_f32_e32 v30, v16, v16
	v_pk_mul_f32 v[28:29], v[28:29], v[54:55] op_sel_hi:[1,0]
	v_pk_mul_f32 v[26:27], v[26:27], v[54:55] op_sel_hi:[1,0]
	v_pk_mul_f32 v[24:25], v[24:25], v[54:55] op_sel_hi:[1,0]
	v_pk_mul_f32 v[22:23], v[22:23], v[54:55] op_sel_hi:[1,0]
	v_pk_mul_f32 v[20:21], v[20:21], v[54:55] op_sel_hi:[1,0]
	v_pk_mul_f32 v[18:19], v[18:19], v[54:55] op_sel_hi:[1,0]
	v_fmac_f32_e32 v30, v17, v17
	v_fmac_f32_e32 v30, v18, v18
	v_fmac_f32_e32 v30, v19, v19
	v_fmac_f32_e32 v30, v20, v20
	v_fmac_f32_e32 v30, v21, v21
	v_fmac_f32_e32 v30, v22, v22
	v_fmac_f32_e32 v30, v23, v23
	v_fmac_f32_e32 v30, v24, v24
	v_fmac_f32_e32 v30, v25, v25
	v_fmac_f32_e32 v30, v26, v26
	v_fmac_f32_e32 v30, v27, v27
	v_fmac_f32_e32 v30, v28, v28
	v_fmac_f32_e32 v30, v29, v29
	v_fmac_f32_e32 v30, v14, v14
	s_waitcnt vmcnt(0)
	v_mov_b32_e32 v31, v52
	v_mov_b32_e32 v52, v53
	s_nop 0
	v_permlane32_swap_b32_e32 v50, v31
	v_permlane32_swap_b32_e32 v51, v52
	v_lshlrev_b32_e32 v55, 16, v31
	v_and_b32_e32 v31, 0xffff0000, v31
	v_lshlrev_b32_e32 v53, 16, v50
	v_and_b32_e32 v50, 0xffff0000, v50
	v_lshlrev_b32_e32 v54, 16, v51
	v_and_b32_e32 v51, 0xffff0000, v51
	v_lshlrev_b32_e32 v56, 16, v52
	v_and_b32_e32 v52, 0xffff0000, v52
	v_mul_f32_e32 v61, 0xbfb8aa3b, v55
	v_mul_f32_e32 v62, 0xbfb8aa3b, v31
	v_mul_f32_e32 v57, 0xbfb8aa3b, v53
	v_mul_f32_e32 v58, 0xbfb8aa3b, v50
	v_mul_f32_e32 v59, 0xbfb8aa3b, v54
	v_mul_f32_e32 v60, 0xbfb8aa3b, v51
	v_mul_f32_e32 v63, 0xbfb8aa3b, v56
	v_mul_f32_e32 v64, 0xbfb8aa3b, v52
	v_exp_f32_e32 v61, v61
	v_exp_f32_e32 v62, v62
	v_exp_f32_e32 v57, v57
	v_exp_f32_e32 v58, v58
	v_exp_f32_e32 v59, v59
	v_exp_f32_e32 v60, v60
	v_exp_f32_e32 v63, v63
	v_exp_f32_e32 v64, v64
	v_add_f32_e32 v61, 1.0, v61
	v_add_f32_e32 v62, 1.0, v62
	v_add_f32_e32 v57, 1.0, v57
	v_add_f32_e32 v58, 1.0, v58
	v_add_f32_e32 v59, 1.0, v59
	v_add_f32_e32 v60, 1.0, v60
	v_add_f32_e32 v63, 1.0, v63
	v_add_f32_e32 v64, 1.0, v64
	v_rcp_f32_e32 v61, v61
	v_rcp_f32_e32 v62, v62
	v_rcp_f32_e32 v57, v57
	v_rcp_f32_e32 v58, v58
	v_rcp_f32_e32 v59, v59
	v_rcp_f32_e32 v60, v60
	v_rcp_f32_e32 v63, v63
	v_rcp_f32_e32 v64, v64
	v_mul_f32_e32 v55, v61, v55
	v_mul_f32_e32 v31, v62, v31
	v_mul_f32_e32 v53, v57, v53
	v_mul_f32_e32 v50, v58, v50
	v_mul_f32_e32 v54, v59, v54
	v_mul_f32_e32 v51, v60, v51
	v_mul_f32_e32 v56, v63, v56
	v_mul_f32_e32 v52, v64, v52
	v_mul_f32_e32 v6, v6, v55
	v_mul_f32_e32 v7, v7, v31
	v_mul_f32_e32 v10, v10, v53
	v_mul_f32_e32 v11, v11, v50
	v_mul_f32_e32 v8, v8, v54
	v_mul_f32_e32 v9, v9, v51
	v_mul_f32_e32 v31, v4, v56
	v_mul_f32_e32 v50, v5, v52
	v_cvt_pk_bf16_f32 v4, v10, v11
	v_cvt_pk_bf16_f32 v5, v8, v9
	v_cvt_pk_bf16_f32 v6, v6, v7
	v_cvt_pk_bf16_f32 v7, v31, v50
	v_fmac_f32_e32 v30, v15, v15
	v_permlane32_swap_b32_e32 v4, v6
	v_permlane32_swap_b32_e32 v5, v7
	global_store_dwordx4 v[48:49], v[4:7], off offset:96
	s_nop 1
	v_mov_b32_e32 v4, v30
	s_nop 1
	v_permlane32_swap_b32_e32 v30, v4
	s_and_saveexec_b64 s[44:45], s[0:1]
	s_cbranch_execz .LBB0_954
	v_add_f32_e32 v6, v30, v4
	v_lshlrev_b64 v[4:5], 5, v[2:3]
	v_lshl_add_u64 v[4:5], s[40:41], 0, v[4:5]
	global_store_dword v[4:5], v6, off
	s_branch .LBB0_954

	.amdhsa_kernel _Z4mega4Args
		.amdhsa_group_segment_fixed_size 0
		.amdhsa_private_segment_fixed_size 0
		.amdhsa_kernarg_size 472
		.amdhsa_user_sgpr_count 2
		.amdhsa_user_sgpr_dispatch_ptr 0
		.amdhsa_user_sgpr_queue_ptr 0
		.amdhsa_user_sgpr_kernarg_segment_ptr 1
		.amdhsa_user_sgpr_dispatch_id 0
		.amdhsa_user_sgpr_kernarg_preload_length 0
		.amdhsa_user_sgpr_kernarg_preload_offset 0
		.amdhsa_user_sgpr_private_segment_size 0
		.amdhsa_uses_dynamic_stack 0
		.amdhsa_enable_private_segment 0
		.amdhsa_system_sgpr_workgroup_id_x 1
		.amdhsa_system_sgpr_workgroup_id_y 0
		.amdhsa_system_sgpr_workgroup_id_z 0
		.amdhsa_system_sgpr_workgroup_info 0
		.amdhsa_system_vgpr_workitem_id 2
		.amdhsa_next_free_vgpr 256
		.amdhsa_next_free_sgpr 102
		.amdhsa_accum_offset 256
		.amdhsa_reserve_vcc 1
		.amdhsa_float_round_mode_32 0
		.amdhsa_float_round_mode_16_64 0
		.amdhsa_float_denorm_mode_32 3
		.amdhsa_float_denorm_mode_16_64 3
		.amdhsa_dx10_clamp 1
		.amdhsa_ieee_mode 1
		.amdhsa_fp16_overflow 0
		.amdhsa_tg_split 0
		.amdhsa_exception_fp_ieee_invalid_op 0
		.amdhsa_exception_fp_denorm_src 0
		.amdhsa_exception_fp_ieee_div_zero 0
		.amdhsa_exception_fp_ieee_overflow 0
		.amdhsa_exception_fp_ieee_underflow 0
		.amdhsa_exception_fp_ieee_inexact 0
		.amdhsa_exception_int_div_zero 0
	.end_amdhsa_kernel

amdhsa.kernels:
  - .agpr_count:     0
    .args:
      - .offset:         0
        .size:           216
        .value_kind:     by_value
      - .offset:         216
        .size:           4
        .value_kind:     hidden_block_count_x
      - .offset:         220
        .size:           4
        .value_kind:     hidden_block_count_y
      - .offset:         224
        .size:           4
        .value_kind:     hidden_block_count_z
      - .offset:         228
        .size:           2
        .value_kind:     hidden_group_size_x
      - .offset:         230
        .size:           2
        .value_kind:     hidden_group_size_y
      - .offset:         232
        .size:           2
        .value_kind:     hidden_group_size_z
      - .offset:         234
        .size:           2
        .value_kind:     hidden_remainder_x
      - .offset:         236
        .size:           2
        .value_kind:     hidden_remainder_y
      - .offset:         238
        .size:           2
        .value_kind:     hidden_remainder_z
      - .offset:         256
        .size:           8
        .value_kind:     hidden_global_offset_x
      - .offset:         264
        .size:           8
        .value_kind:     hidden_global_offset_y
      - .offset:         272
        .size:           8
        .value_kind:     hidden_global_offset_z
      - .offset:         280
        .size:           2
        .value_kind:     hidden_grid_dims
      - .offset:         304
        .size:           8
        .value_kind:     hidden_multigrid_sync_arg
      - .offset:         336
        .size:           4
        .value_kind:     hidden_dynamic_lds_size
    .group_segment_fixed_size: 0
    .kernarg_segment_align: 8
    .kernarg_segment_size: 472
    .language:       OpenCL C
    .language_version:
      - 2
      - 0
    .max_flat_workgroup_size: 512
    .name:           _Z4mega4Args
    .private_segment_fixed_size: 0
    .sgpr_count:     108
    .sgpr_spill_count: 50
    .symbol:         _Z4mega4Args.kd
    .uniform_work_group_size: 1
    .uses_dynamic_stack: false
    .vgpr_count:     256
    .vgpr_spill_count: 0
    .wavefront_size: 64
